# v16 + LayerNorm shift/scale reload (on batch change) issued at the row top instead of right before its use
# speedup vs baseline: 1.0054x; 1.0054x over previous
; DI unsigned pkh2(float lo, float hi) { return __builtin_bit_cast(unsigned, __builtin_amdgcn_cvt_pkrtz(lo, hi)); }
; DI float hlo(unsigned u) { return (float)__builtin_bit_cast(f16x2_t, u).x; }
; DI void lnmod_phase(const Args& A, LAS unsigned char* lds, int tid, int bid, int G, bool init, int l_norm, int i_norm, int l_mod, int i_mod, bool want_dt, int nrows, bool ctx_partial, const float* gprev, const float* bprev) {
;     ...
;         for (int j = 0; j < 4; ++j) v[j] = init ? fn[j] : (f32x4){hlo(un[j].x), hhi(un[j].x), hlo(un[j].y), hhi(un[j].y)};
;         { const int rown = row + G * 8;
;           if (rown < nrows) {
;               if (init) { const float* xin = rown < M_LAT ? A.in[I_X] + (size_t)rown * DM : A.in[I_CTX] + (size_t)(rown - M_LAT) * DM;
; #pragma unroll
;                   for (int j = 0; j < 4; ++j) fn[j] = *(const f32x4*)(xin + 256 * j + 4 * lane); }
;               else {
; #pragma unroll
;                   for (int j = 0; j < 4; ++j) un[j] = *(const u32x2*)(X16 + (size_t)rown * DM + 256 * j + 4 * lane); } } }
;         f32x2* STAT = (f32x2*)(A.ws + WS_STAT);
;         if (ctx_partial && row >= M_LAT) {
;             { const f32x2 st = STAT[row];
; #pragma unroll
;               for (int j = 0; j < 4; ++j) v[j] = (v[j] - st.x) * st.y * *(const f32x4*)(gprev + 256 * j + 4 * lane) + *(const f32x4*)(bprev + 256 * j + 4 * lane); }
;             const float* t0 = (const float*)(A.ws + WS_T) + (size_t)(row - M_LAT) * DM; const float* t1 = t0 + (size_t)M_CTX * DM; const float* t2 = t1 + (size_t)M_CTX * DM; const float* t3 = t2 + (size_t)M_CTX * DM;
; #pragma unroll
;             for (int j = 0; j < 4; ++j) { v[j] = v[j] * ALPHA + (*(const f32x4*)(t0 + 256 * j + 4 * lane) + *(const f32x4*)(t1 + 256 * j + 4 * lane)) + (*(const f32x4*)(t2 + 256 * j + 4 * lane) + *(const f32x4*)(t3 + 256 * j + 4 * lane)); u32x2 w_; w_.x = pkh2(v[j].x, v[j].y); w_.y = pkh2(v[j].z, v[j].w); *(u32x2*)(xout + 256 * j + 4 * lane) = w_; }
;     ...
;             const int mi = row < M_LAT ? (row >> 12) : 8;
;             const float* mp = MOD + ((size_t)l_mod * 9 + mi) * 9216 + i_mod * 3072;
;             if (mi != mi_cur) { mi_cur = mi;
; #pragma unroll
;                 for (int j = 0; j < 4; ++j) { shv[j] = *(const f32x4*)(mp + 256 * j + 4 * lane); sclv[j] = *(const f32x4*)(mp + 1024 + 256 * j + 4 * lane) + 1.0f; } }
.Llnmi_done0:
	s_or_b64 exec, exec, s[78:79]
	v_cvt_f32_f16_sdwa v106, v92 dst_sel:DWORD dst_unused:UNUSED_PAD src0_sel:WORD_1
	v_cvt_f32_f16_e32 v90, v92
	v_cvt_f32_f16_sdwa v91, v93 dst_sel:DWORD dst_unused:UNUSED_PAD src0_sel:WORD_1
	v_cvt_f32_f16_e32 v107, v93
	v_cvt_f32_f16_sdwa v102, v94 dst_sel:DWORD dst_unused:UNUSED_PAD src0_sel:WORD_1
	v_cvt_f32_f16_e32 v92, v94
	v_cvt_f32_f16_sdwa v93, v95 dst_sel:DWORD dst_unused:UNUSED_PAD src0_sel:WORD_1
	v_cvt_f32_f16_e32 v103, v95
	v_cvt_f32_f16_sdwa v97, v98 dst_sel:DWORD dst_unused:UNUSED_PAD src0_sel:WORD_1
	v_cvt_f32_f16_e32 v96, v98
	v_cvt_f32_f16_sdwa v95, v99 dst_sel:DWORD dst_unused:UNUSED_PAD src0_sel:WORD_1
	v_cvt_f32_f16_e32 v94, v99
	v_cvt_f32_f16_sdwa v104, v88 dst_sel:DWORD dst_unused:UNUSED_PAD src0_sel:WORD_1
	v_cvt_f32_f16_e32 v100, v88
	v_cvt_f32_f16_sdwa v108, v89 dst_sel:DWORD dst_unused:UNUSED_PAD src0_sel:WORD_1
	v_cvt_f32_f16_e32 v98, v89
	v_readlane_b32 s36, v253, 23
	s_movk_i32 s6, 0x7fff
	v_readlane_b32 s38, v253, 25
	v_readlane_b32 s39, v253, 26
	v_cmp_lt_i32_e32 vcc, s6, v86
	v_readlane_b32 s37, v253, 24
	v_lshl_add_u64 v[88:89], s[38:39], 0, v[64:65]
	s_and_saveexec_b64 s[6:7], vcc
	s_cbranch_execz .LBB0_209
	v_readlane_b32 s38, v253, 25
	v_readlane_b32 s39, v253, 26
	v_add_u32_e32 v146, 0xffff8000, v86
	s_nop 1
	v_lshl_add_u64 v[110:111], s[38:39], 0, v[74:75]
	global_load_dwordx2 v[122:123], v[110:111], off
	v_readlane_b32 s36, v251, 61
	v_readlane_b32 s37, v251, 62
	s_mov_b32 s19, 0x800000
	global_load_dwordx4 v[172:175], v[68:69], off
	global_load_dwordx4 v[118:121], v[70:71], off
	global_load_dwordx4 v[176:179], v[68:69], off offset:1024
	global_load_dwordx4 v[180:183], v[70:71], off offset:1024
	global_load_dwordx4 v[184:187], v[68:69], off offset:2048
	global_load_dwordx4 v[188:191], v[70:71], off offset:2048
	global_load_dwordx4 v[192:195], v[68:69], off offset:3072
	global_load_dwordx4 v[196:199], v[70:71], off offset:3072
	s_waitcnt vmcnt(8)
	v_sub_f32_e32 v111, v106, v122
	v_sub_f32_e32 v110, v90, v122
	v_sub_f32_e32 v90, v107, v122
	v_pk_mul_f32 v[106:107], v[122:123], v[110:111] op_sel:[1,0]
	v_sub_f32_e32 v91, v91, v122
	v_pk_mul_f32 v[90:91], v[122:123], v[90:91] op_sel:[1,0]
	v_sub_f32_e32 v93, v93, v122
	v_sub_f32_e32 v97, v97, v122
	v_sub_f32_e32 v96, v96, v122
	v_sub_f32_e32 v95, v95, v122
	v_sub_f32_e32 v94, v94, v122
	v_sub_f32_e32 v101, v104, v122
	v_sub_f32_e32 v100, v100, v122
	v_sub_f32_e32 v99, v108, v122
	v_sub_f32_e32 v98, v98, v122
	v_pk_mul_f32 v[108:109], v[122:123], v[100:101] op_sel:[1,0]
	s_waitcnt vmcnt(6)
	v_pk_fma_f32 v[126:127], v[172:173], v[106:107], v[118:119]
	v_pk_fma_f32 v[90:91], v[174:175], v[90:91], v[120:121]
	v_sub_f32_e32 v107, v102, v122
	v_sub_f32_e32 v106, v92, v122
	v_sub_f32_e32 v92, v103, v122
	v_pk_mul_f32 v[102:103], v[122:123], v[92:93] op_sel:[1,0]
	v_pk_mul_f32 v[92:93], v[122:123], v[106:107] op_sel:[1,0]
	v_pk_mul_f32 v[106:107], v[122:123], v[96:97] op_sel:[1,0]
	s_waitcnt vmcnt(4)
	v_pk_fma_f32 v[92:93], v[92:93], v[176:177], v[180:181]
	v_pk_fma_f32 v[176:177], v[102:103], v[178:179], v[182:183]
	v_pk_mul_f32 v[102:103], v[122:123], v[94:95] op_sel:[1,0]
	s_waitcnt vmcnt(2)
	v_pk_fma_f32 v[184:185], v[106:107], v[184:185], v[188:189]
	v_pk_fma_f32 v[186:187], v[102:103], v[186:187], v[190:191]
	v_pk_mul_f32 v[106:107], v[122:123], v[98:99] op_sel:[1,0]
	s_waitcnt vmcnt(0)
	v_pk_fma_f32 v[192:193], v[108:109], v[192:193], v[196:197]
	v_lshlrev_b64 v[102:103], 12, v[146:147]
	v_lshl_add_u64 v[102:103], s[36:37], 0, v[102:103]
	v_lshlrev_b32_e32 v146, 2, v66
	v_lshl_add_u64 v[108:109], v[102:103], 0, v[146:147]
	v_add_co_u32_e32 v172, vcc, s19, v108
	global_load_dwordx4 v[118:121], v[108:109], off
	s_nop 1
	v_addc_co_u32_e32 v173, vcc, 0, v109, vcc
	global_load_dwordx4 v[122:125], v[172:173], off
	s_mov_b64 s[36:37], 0x800000
	v_lshl_add_u64 v[112:113], v[108:109], 0, s[36:37]
	s_mov_b64 s[36:37], 0x1000000
	v_lshl_add_u64 v[174:175], v[108:109], 0, s[36:37]
	s_mov_b64 s[36:37], 0x1800000
	v_lshl_add_u64 v[180:181], v[108:109], 0, s[36:37]
	s_mov_b32 s19, 0x1000000
	v_add_co_u32_e32 v182, vcc, s19, v108
	s_mov_b32 s19, 0x1800000
	s_nop 1
	v_addc_co_u32_e32 v183, vcc, 0, v109, vcc
	global_load_dwordx4 v[188:191], v[182:183], off
	v_add_co_u32_e32 v200, vcc, s19, v108
	s_nop 1
	v_addc_co_u32_e32 v201, vcc, 0, v109, vcc
	global_load_dwordx4 v[202:205], v[200:201], off
	global_load_dwordx4 v[218:221], v[108:109], off offset:1024
	global_load_dwordx4 v[222:225], v[112:113], off offset:1024
	global_load_dwordx4 v[226:229], v[174:175], off offset:1024
	global_load_dwordx4 v[230:233], v[180:181], off offset:1024
	s_nop 0
	v_pk_fma_f32 v[194:195], v[106:107], v[194:195], v[198:199]
	s_mov_b32 s36, 0x3fd744fd
	s_waitcnt vmcnt(6)
; DI unsigned pkh2(float lo, float hi) { return __builtin_bit_cast(unsigned, __builtin_amdgcn_cvt_pkrtz(lo, hi)); }
; DI void lnmod_phase(const Args& A, LAS unsigned char* lds, int tid, int bid, int G, bool init, int l_norm, int i_norm, int l_mod, int i_mod, bool want_dt, int nrows, bool ctx_partial, const float* gprev, const float* bprev) {
;     ...
;             const float* t0 = (const float*)(A.ws + WS_T) + (size_t)(row - M_LAT) * DM; const float* t1 = t0 + (size_t)M_CTX * DM; const float* t2 = t1 + (size_t)M_CTX * DM; const float* t3 = t2 + (size_t)M_CTX * DM;
; #pragma unroll
;             for (int j = 0; j < 4; ++j) { v[j] = v[j] * ALPHA + (*(const f32x4*)(t0 + 256 * j + 4 * lane) + *(const f32x4*)(t1 + 256 * j + 4 * lane)) + (*(const f32x4*)(t2 + 256 * j + 4 * lane) + *(const f32x4*)(t3 + 256 * j + 4 * lane)); u32x2 w_; w_.x = pkh2(v[j].x, v[j].y); w_.y = pkh2(v[j].z, v[j].w); *(u32x2*)(xout + 256 * j + 4 * lane) = w_; }
	v_pk_add_f32 v[172:173], v[120:121], v[124:125]
	s_nop 0
	v_pk_fma_f32 v[90:91], v[90:91], s[36:37], v[172:173] op_sel_hi:[1,0,1]
	s_nop 0
	v_pk_add_f32 v[114:115], v[118:119], v[122:123]
	v_pk_fma_f32 v[114:115], v[126:127], s[36:37], v[114:115] op_sel_hi:[1,0,1]
	s_nop 0
	s_mov_b32 s19, 0x21200000
	s_waitcnt vmcnt(4)
	v_pk_add_f32 v[200:201], v[190:191], v[204:205]
	v_pk_add_f32 v[188:189], v[188:189], v[202:203]
	v_pk_add_f32 v[200:201], v[90:91], v[200:201]
	v_pk_add_f32 v[90:91], v[114:115], v[188:189]
	v_add_co_u32_e32 v114, vcc, s19, v88
	v_cvt_pkrtz_f16_f32 v188, v90, v91
	v_cvt_pkrtz_f16_f32 v189, v200, v201
	v_addc_co_u32_e32 v115, vcc, 0, v89, vcc
	global_store_dwordx2 v[114:115], v[188:189], off
	s_nop 0
	s_waitcnt vmcnt(2)
	v_pk_add_f32 v[220:221], v[220:221], v[224:225]
	v_pk_add_f32 v[218:219], v[218:219], v[222:223]
	v_pk_fma_f32 v[176:177], v[176:177], s[36:37], v[220:221] op_sel_hi:[1,0,1]
	v_pk_fma_f32 v[92:93], v[92:93], s[36:37], v[218:219] op_sel_hi:[1,0,1]
	s_waitcnt vmcnt(0)
	v_pk_add_f32 v[228:229], v[228:229], v[232:233]
	v_pk_add_f32 v[226:227], v[226:227], v[230:231]
	v_pk_add_f32 v[126:127], v[176:177], v[228:229]
	v_pk_add_f32 v[92:93], v[92:93], v[226:227]
	v_cvt_pkrtz_f16_f32 v177, v126, v127
	v_cvt_pkrtz_f16_f32 v176, v92, v93
	global_store_dwordx2 v[114:115], v[176:177], off offset:512
	global_load_dwordx4 v[118:121], v[108:109], off offset:2048
	global_load_dwordx4 v[122:125], v[112:113], off offset:2048
	global_load_dwordx4 v[176:179], v[174:175], off offset:2048
	global_load_dwordx4 v[188:191], v[180:181], off offset:2048
	global_load_dwordx4 v[196:199], v[108:109], off offset:3072
	global_load_dwordx4 v[202:205], v[112:113], off offset:3072
	global_load_dwordx4 v[218:221], v[174:175], off offset:3072
	global_load_dwordx4 v[104:107], v[180:181], off offset:3072
	s_waitcnt vmcnt(6)
	v_pk_add_f32 v[110:111], v[120:121], v[124:125]
	v_pk_add_f32 v[118:119], v[118:119], v[122:123]
	v_pk_fma_f32 v[110:111], v[186:187], s[36:37], v[110:111] op_sel_hi:[1,0,1]
	v_pk_fma_f32 v[122:123], v[184:185], s[36:37], v[118:119] op_sel_hi:[1,0,1]
	s_waitcnt vmcnt(4)
	v_pk_add_f32 v[178:179], v[178:179], v[190:191]
	v_pk_add_f32 v[188:189], v[176:177], v[188:189]
	v_pk_add_f32 v[176:177], v[110:111], v[178:179]
	v_pk_add_f32 v[178:179], v[122:123], v[188:189]
	v_cvt_pkrtz_f16_f32 v111, v176, v177
	v_cvt_pkrtz_f16_f32 v110, v178, v179
	global_store_dwordx2 v[114:115], v[110:111], off offset:1024
	s_nop 0
	s_waitcnt vmcnt(2)
	v_pk_add_f32 v[198:199], v[198:199], v[204:205]
	v_pk_add_f32 v[196:197], v[196:197], v[202:203]
	v_pk_fma_f32 v[198:199], v[194:195], s[36:37], v[198:199] op_sel_hi:[1,0,1]
	v_pk_fma_f32 v[196:197], v[192:193], s[36:37], v[196:197] op_sel_hi:[1,0,1]
	s_nop 0
	s_waitcnt vmcnt(0)
	v_pk_add_f32 v[220:221], v[220:221], v[106:107]
	v_pk_add_f32 v[104:105], v[218:219], v[104:105]
	v_pk_add_f32 v[218:219], v[198:199], v[220:221]
	v_pk_add_f32 v[220:221], v[196:197], v[104:105]
	v_cvt_pkrtz_f16_f32 v105, v218, v219
	v_cvt_pkrtz_f16_f32 v104, v220, v221
	global_store_dwordx2 v[114:115], v[104:105], off offset:1536
	v_mov_b32_e32 v106, v91
	v_mov_b32_e32 v107, v200
	v_mov_b32_e32 v91, v201
	v_mov_b32_e32 v200, v93
	v_mov_b32_e32 v201, v126
	v_mov_b32_e32 v93, v127
	v_mov_b32_e32 v104, v221
	v_mov_b32_e32 v196, v219
	v_mov_b32_e32 v94, v176
	v_mov_b32_e32 v95, v177
	v_mov_b32_e32 v96, v178
	v_mov_b32_e32 v97, v179
	v_mov_b32_e32 v98, v218
	v_mov_b32_e32 v100, v220
	v_mov_b32_e32 v102, v200
	v_mov_b32_e32 v103, v201
	v_mov_b32_e32 v108, v196

; DI void lnmod_phase(const Args& A, LAS unsigned char* lds, int tid, int bid, int G, bool init, int l_norm, int i_norm, int l_mod, int i_mod, bool want_dt, int nrows, bool ctx_partial, const float* gprev, const float* bprev) {
;     ...
;         if (l_mod >= 0) {
;             const int mi = row < M_LAT ? (row >> 12) : 8;
;             const float* mp = MOD + ((size_t)l_mod * 9 + mi) * 9216 + i_mod * 3072;
;             if (mi != mi_cur) { mi_cur = mi;
; #pragma unroll
;                 for (int j = 0; j < 4; ++j) { shv[j] = *(const f32x4*)(mp + 256 * j + 4 * lane); sclv[j] = *(const f32x4*)(mp + 1024 + 256 * j + 4 * lane) + 1.0f; } }
.LBB0_212:
	s_or_b64 exec, exec, s[6:7]
	s_waitcnt vmcnt(0)
	v_mov_b32_e32 v172, v78
	v_mov_b32_e32 v173, v79
	v_mov_b32_e32 v174, v80
	v_mov_b32_e32 v175, v81
	v_mov_b32_e32 v176, v82
	v_mov_b32_e32 v177, v83
	v_mov_b32_e32 v178, v84
	v_mov_b32_e32 v179, v85
	v_min_i32_e32 v86, 0x8000, v86
	v_ashrrev_i32_e32 v86, 12, v86
	s_mov_b64 vcc, s[76:77]
	s_and_saveexec_b64 s[6:7], vcc
	s_cbranch_execz .LBB0_214
	v_readlane_b32 s36, v251, 59
	v_readlane_b32 s37, v251, 60
	s_waitcnt vmcnt(7)
	v_pk_add_f32 v[50:51], v[50:51], 1.0 op_sel_hi:[1,0]
	v_pk_add_f32 v[48:49], v[48:49], 1.0 op_sel_hi:[1,0]
	s_waitcnt vmcnt(6)
	v_pk_add_f32 v[54:55], v[54:55], 1.0 op_sel_hi:[1,0]
	v_pk_add_f32 v[52:53], v[52:53], 1.0 op_sel_hi:[1,0]
	s_waitcnt vmcnt(5)
	v_pk_add_f32 v[58:59], v[58:59], 1.0 op_sel_hi:[1,0]
	v_pk_add_f32 v[56:57], v[56:57], 1.0 op_sel_hi:[1,0]
	s_waitcnt vmcnt(4)
	v_pk_add_f32 v[62:63], v[62:63], 1.0 op_sel_hi:[1,0]
	v_pk_add_f32 v[60:61], v[60:61], 1.0 op_sel_hi:[1,0]

; DI float hlo(unsigned u) { return (float)__builtin_bit_cast(f16x2_t, u).x; }
; DI float hhi(unsigned u) { return (float)__builtin_bit_cast(f16x2_t, u).y; }
; DI void lnmod_phase(const Args& A, LAS unsigned char* lds, int tid, int bid, int G, bool init, int l_norm, int i_norm, int l_mod, int i_mod, bool want_dt, int nrows, bool ctx_partial, const float* gprev, const float* bprev) {
;     ...
;         for (int j = 0; j < 4; ++j) v[j] = init ? fn[j] : (f32x4){hlo(un[j].x), hhi(un[j].x), hlo(un[j].y), hhi(un[j].y)};
;         { const int rown = row + G * 8;
;           if (rown < nrows) {
;               if (init) { const float* xin = rown < M_LAT ? A.in[I_X] + (size_t)rown * DM : A.in[I_CTX] + (size_t)(rown - M_LAT) * DM;
; #pragma unroll
;                   for (int j = 0; j < 4; ++j) fn[j] = *(const f32x4*)(xin + 256 * j + 4 * lane); }
;               else {
; #pragma unroll
;                   for (int j = 0; j < 4; ++j) un[j] = *(const u32x2*)(X16 + (size_t)rown * DM + 256 * j + 4 * lane); } } }
;         f32x2* STAT = (f32x2*)(A.ws + WS_STAT);
;         if (ctx_partial && row >= M_LAT) {
;             { const f32x2 st = STAT[row];
; #pragma unroll
;               for (int j = 0; j < 4; ++j) v[j] = (v[j] - st.x) * st.y * *(const f32x4*)(gprev + 256 * j + 4 * lane) + *(const f32x4*)(bprev + 256 * j + 4 * lane); }
.Llnmi_skip1:
	v_cvt_f32_f16_sdwa v108, v66 dst_sel:DWORD dst_unused:UNUSED_PAD src0_sel:WORD_1
	v_cvt_f32_f16_e32 v64, v66
	v_cvt_f32_f16_sdwa v65, v67 dst_sel:DWORD dst_unused:UNUSED_PAD src0_sel:WORD_1
	v_cvt_f32_f16_e32 v109, v67
	v_cvt_f32_f16_sdwa v66, v72 dst_sel:DWORD dst_unused:UNUSED_PAD src0_sel:WORD_1
	v_cvt_f32_f16_e32 v68, v72
	v_cvt_f32_f16_sdwa v69, v73 dst_sel:DWORD dst_unused:UNUSED_PAD src0_sel:WORD_1
	v_cvt_f32_f16_e32 v67, v73
	v_cvt_f32_f16_sdwa v73, v70 dst_sel:DWORD dst_unused:UNUSED_PAD src0_sel:WORD_1
	v_cvt_f32_f16_e32 v72, v70
	v_cvt_f32_f16_sdwa v75, v71 dst_sel:DWORD dst_unused:UNUSED_PAD src0_sel:WORD_1
	v_cvt_f32_f16_e32 v74, v71
	v_cvt_f32_f16_sdwa v70, v76 dst_sel:DWORD dst_unused:UNUSED_PAD src0_sel:WORD_1
	v_cvt_f32_f16_e32 v76, v76
	v_cvt_f32_f16_sdwa v106, v77 dst_sel:DWORD dst_unused:UNUSED_PAD src0_sel:WORD_1
	v_cvt_f32_f16_e32 v78, v77
	s_movk_i32 s4, 0x7fff
	v_cmp_lt_i32_e32 vcc, s4, v118
	v_readlane_b32 s4, v253, 37
	v_readlane_b32 s40, v253, 23
	v_readlane_b32 s5, v253, 38
	v_readlane_b32 s42, v253, 25
	v_readlane_b32 s43, v253, 26
	s_and_b64 s[36:37], s[4:5], vcc
	v_readlane_b32 s41, v253, 24
	v_lshl_add_u64 v[104:105], s[42:43], 0, v[82:83]
	s_and_saveexec_b64 s[4:5], s[36:37]
	s_cbranch_execz .LBB0_233
	v_readlane_b32 s38, v253, 25
	v_readlane_b32 s39, v253, 26
	v_add_u32_e32 v146, 0xffff8000, v118
	s_nop 1
	v_lshl_add_u64 v[110:111], s[38:39], 0, v[92:93]
	global_load_dwordx2 v[120:121], v[110:111], off
	v_readlane_b32 s36, v251, 61
	v_readlane_b32 s37, v251, 62
	s_mov_b32 s7, 0x800000
	global_load_dwordx4 v[130:133], v[86:87], off
	global_load_dwordx4 v[112:115], v[88:89], off
	global_load_dwordx4 v[134:137], v[86:87], off offset:1024
	global_load_dwordx4 v[138:141], v[88:89], off offset:1024
	global_load_dwordx4 v[154:157], v[86:87], off offset:2048
	global_load_dwordx4 v[160:163], v[88:89], off offset:2048
	global_load_dwordx4 v[164:167], v[86:87], off offset:3072
	global_load_dwordx4 v[168:171], v[88:89], off offset:3072
	s_waitcnt vmcnt(8)
	v_sub_f32_e32 v111, v108, v120
	v_sub_f32_e32 v110, v64, v120
	v_sub_f32_e32 v64, v109, v120
	v_pk_mul_f32 v[122:123], v[120:121], v[110:111] op_sel:[1,0]
	v_sub_f32_e32 v65, v65, v120
	v_pk_mul_f32 v[64:65], v[120:121], v[64:65] op_sel:[1,0]
	v_sub_f32_e32 v69, v69, v120
	s_waitcnt vmcnt(6)
	v_pk_fma_f32 v[114:115], v[132:133], v[64:65], v[114:115]
	v_sub_f32_e32 v65, v66, v120
	v_sub_f32_e32 v64, v68, v120
	v_sub_f32_e32 v68, v67, v120
	v_pk_fma_f32 v[128:129], v[130:131], v[122:123], v[112:113]
	v_pk_mul_f32 v[112:113], v[120:121], v[68:69] op_sel:[1,0]
	v_pk_mul_f32 v[68:69], v[120:121], v[64:65] op_sel:[1,0]
	s_waitcnt vmcnt(4)
	v_pk_fma_f32 v[68:69], v[68:69], v[134:135], v[138:139]
	v_pk_fma_f32 v[138:139], v[112:113], v[136:137], v[140:141]
	v_sub_f32_e32 v135, v73, v120
	v_sub_f32_e32 v134, v72, v120
	v_sub_f32_e32 v137, v75, v120
	v_sub_f32_e32 v136, v74, v120
	v_pk_mul_f32 v[140:141], v[120:121], v[136:137] op_sel:[1,0]
	v_pk_mul_f32 v[112:113], v[120:121], v[134:135] op_sel:[1,0]
	s_waitcnt vmcnt(2)
	v_pk_fma_f32 v[160:161], v[112:113], v[154:155], v[160:161]
	v_pk_fma_f32 v[162:163], v[140:141], v[156:157], v[162:163]
	v_sub_f32_e32 v154, v76, v120
	v_sub_f32_e32 v156, v78, v120
	v_sub_f32_e32 v155, v70, v120
	v_sub_f32_e32 v157, v106, v120
	v_pk_mul_f32 v[154:155], v[120:121], v[154:155] op_sel:[1,0]
	v_pk_mul_f32 v[70:71], v[120:121], v[156:157] op_sel:[1,0]
	s_waitcnt vmcnt(0)
; DI unsigned pkh2(float lo, float hi) { return __builtin_bit_cast(unsigned, __builtin_amdgcn_cvt_pkrtz(lo, hi)); }
; DI void lnmod_phase(const Args& A, LAS unsigned char* lds, int tid, int bid, int G, bool init, int l_norm, int i_norm, int l_mod, int i_mod, bool want_dt, int nrows, bool ctx_partial, const float* gprev, const float* bprev) {
;     ...
;             const float* t0 = (const float*)(A.ws + WS_T) + (size_t)(row - M_LAT) * DM; const float* t1 = t0 + (size_t)M_CTX * DM; const float* t2 = t1 + (size_t)M_CTX * DM; const float* t3 = t2 + (size_t)M_CTX * DM;
; #pragma unroll
;             for (int j = 0; j < 4; ++j) { v[j] = v[j] * ALPHA + (*(const f32x4*)(t0 + 256 * j + 4 * lane) + *(const f32x4*)(t1 + 256 * j + 4 * lane)) + (*(const f32x4*)(t2 + 256 * j + 4 * lane) + *(const f32x4*)(t3 + 256 * j + 4 * lane)); u32x2 w_; w_.x = pkh2(v[j].x, v[j].y); w_.y = pkh2(v[j].z, v[j].w); *(u32x2*)(xout + 256 * j + 4 * lane) = w_; }
	v_pk_fma_f32 v[156:157], v[154:155], v[164:165], v[168:169]
	v_lshlrev_b64 v[64:65], 12, v[146:147]
	v_lshl_add_u64 v[64:65], s[36:37], 0, v[64:65]
	v_lshlrev_b32_e32 v146, 2, v84
	v_lshl_add_u64 v[110:111], v[64:65], 0, v[146:147]
	v_add_co_u32_e32 v130, vcc, s7, v110
	global_load_dwordx4 v[120:123], v[110:111], off
	s_nop 1
	v_addc_co_u32_e32 v131, vcc, 0, v111, vcc
	global_load_dwordx4 v[124:127], v[130:131], off
	s_mov_b64 s[36:37], 0x800000
	v_lshl_add_u64 v[132:133], v[110:111], 0, s[36:37]
	s_mov_b64 s[36:37], 0x1000000
	v_lshl_add_u64 v[76:77], v[110:111], 0, s[36:37]
	s_mov_b64 s[36:37], 0x1800000
	v_lshl_add_u64 v[134:135], v[110:111], 0, s[36:37]
	s_mov_b32 s7, 0x1000000
	v_add_co_u32_e32 v136, vcc, s7, v110
	s_mov_b32 s7, 0x1800000
	s_nop 1
	v_addc_co_u32_e32 v137, vcc, 0, v111, vcc
	global_load_dwordx4 v[172:175], v[136:137], off
	v_add_co_u32_e32 v142, vcc, s7, v110
	s_nop 1
	v_addc_co_u32_e32 v143, vcc, 0, v111, vcc
	global_load_dwordx4 v[176:179], v[142:143], off
	global_load_dwordx4 v[180:183], v[110:111], off offset:1024
	global_load_dwordx4 v[184:187], v[132:133], off offset:1024
	global_load_dwordx4 v[188:191], v[76:77], off offset:1024
	global_load_dwordx4 v[192:195], v[134:135], off offset:1024
	global_load_dwordx4 v[196:199], v[110:111], off offset:2048
	global_load_dwordx4 v[200:203], v[132:133], off offset:2048
	global_load_dwordx4 v[204:207], v[76:77], off offset:2048
	global_load_dwordx4 v[218:221], v[134:135], off offset:2048
	global_load_dwordx4 v[222:225], v[110:111], off offset:3072
	global_load_dwordx4 v[226:229], v[132:133], off offset:3072
	global_load_dwordx4 v[230:233], v[76:77], off offset:3072
	global_load_dwordx4 v[234:237], v[134:135], off offset:3072
	s_nop 0
	v_pk_fma_f32 v[70:71], v[70:71], v[166:167], v[170:171]
	s_mov_b32 s36, 0x3fd744fd
	s_waitcnt vmcnt(14)
	v_pk_add_f32 v[130:131], v[122:123], v[126:127]
	v_pk_add_f32 v[106:107], v[120:121], v[124:125]
	v_pk_fma_f32 v[130:131], v[114:115], s[36:37], v[130:131] op_sel_hi:[1,0,1]
	v_pk_fma_f32 v[114:115], v[128:129], s[36:37], v[106:107] op_sel_hi:[1,0,1]
	s_nop 0
	s_mov_b32 s7, 0x21200000
	s_nop 0
	s_waitcnt vmcnt(12)
	v_pk_add_f32 v[142:143], v[174:175], v[178:179]
	v_pk_add_f32 v[172:173], v[172:173], v[176:177]
	v_pk_add_f32 v[142:143], v[130:131], v[142:143]
	v_pk_add_f32 v[130:131], v[114:115], v[172:173]
	v_add_co_u32_e32 v114, vcc, s7, v104
	v_cvt_pkrtz_f16_f32 v172, v130, v131
	v_cvt_pkrtz_f16_f32 v173, v142, v143
	v_addc_co_u32_e32 v115, vcc, 0, v105, vcc
	global_store_dwordx2 v[114:115], v[172:173], off
	s_nop 0
	s_waitcnt vmcnt(10)
	v_pk_add_f32 v[182:183], v[182:183], v[186:187]
	v_pk_add_f32 v[180:181], v[180:181], v[184:185]
	v_pk_fma_f32 v[138:139], v[138:139], s[36:37], v[182:183] op_sel_hi:[1,0,1]
	v_pk_fma_f32 v[68:69], v[68:69], s[36:37], v[180:181] op_sel_hi:[1,0,1]
	s_waitcnt vmcnt(8)
	v_pk_add_f32 v[190:191], v[190:191], v[194:195]
	v_pk_add_f32 v[188:189], v[188:189], v[192:193]
	v_pk_add_f32 v[128:129], v[138:139], v[190:191]
	v_pk_add_f32 v[68:69], v[68:69], v[188:189]
	v_cvt_pkrtz_f16_f32 v139, v128, v129
	v_cvt_pkrtz_f16_f32 v138, v68, v69
	global_store_dwordx2 v[114:115], v[138:139], off offset:512
	s_waitcnt vmcnt(6)
	v_pk_add_f32 v[138:139], v[198:199], v[202:203]
	v_pk_add_f32 v[196:197], v[196:197], v[200:201]
	v_pk_fma_f32 v[138:139], v[162:163], s[36:37], v[138:139] op_sel_hi:[1,0,1]
	v_pk_fma_f32 v[200:201], v[160:161], s[36:37], v[196:197] op_sel_hi:[1,0,1]
	s_waitcnt vmcnt(4)
	v_pk_add_f32 v[206:207], v[206:207], v[220:221]
	v_pk_add_f32 v[204:205], v[204:205], v[218:219]
	v_pk_add_f32 v[206:207], v[138:139], v[206:207]
	v_pk_add_f32 v[204:205], v[200:201], v[204:205]
	v_cvt_pkrtz_f16_f32 v139, v206, v207
	v_cvt_pkrtz_f16_f32 v138, v204, v205
	global_store_dwordx2 v[114:115], v[138:139], off offset:1024
	s_nop 0
	s_waitcnt vmcnt(2)
	v_pk_add_f32 v[224:225], v[224:225], v[228:229]
	v_pk_add_f32 v[222:223], v[222:223], v[226:227]
	v_pk_fma_f32 v[70:71], v[70:71], s[36:37], v[224:225] op_sel_hi:[1,0,1]
	v_pk_fma_f32 v[156:157], v[156:157], s[36:37], v[222:223] op_sel_hi:[1,0,1]
	s_nop 0
	s_waitcnt vmcnt(0)
	v_pk_add_f32 v[236:237], v[232:233], v[236:237]
	v_pk_add_f32 v[234:235], v[230:231], v[234:235]
	v_pk_add_f32 v[236:237], v[70:71], v[236:237]
	v_pk_add_f32 v[234:235], v[156:157], v[234:235]
	v_cvt_pkrtz_f16_f32 v157, v236, v237
	v_cvt_pkrtz_f16_f32 v156, v234, v235
	global_store_dwordx2 v[114:115], v[156:157], off offset:1536
	v_mov_b32_e32 v230, v131
	v_mov_b32_e32 v231, v142
	v_mov_b32_e32 v131, v143
	v_mov_b32_e32 v156, v69
	v_mov_b32_e32 v157, v128
	v_mov_b32_e32 v69, v129
	v_mov_b32_e32 v70, v235
	v_mov_b32_e32 v142, v237
	v_mov_b32_e32 v64, v130
	v_mov_b32_e32 v65, v131
	v_mov_b32_e32 v66, v156
	v_mov_b32_e32 v67, v157
	v_mov_b32_e32 v72, v204
	v_mov_b32_e32 v73, v205
	v_mov_b32_e32 v74, v206
	v_mov_b32_e32 v75, v207
	v_mov_b32_e32 v76, v234
	v_mov_b32_e32 v78, v236
	v_mov_b32_e32 v106, v142
	v_mov_b32_e32 v108, v230
	v_mov_b32_e32 v109, v231

; DI void lnmod_phase(const Args& A, LAS unsigned char* lds, int tid, int bid, int G, bool init, int l_norm, int i_norm, int l_mod, int i_mod, bool want_dt, int nrows, bool ctx_partial, const float* gprev, const float* bprev) {
;     ...
;         if (l_mod >= 0) {
;             const int mi = row < M_LAT ? (row >> 12) : 8;
;             const float* mp = MOD + ((size_t)l_mod * 9 + mi) * 9216 + i_mod * 3072;
;             if (mi != mi_cur) { mi_cur = mi;
; #pragma unroll
;                 for (int j = 0; j < 4; ++j) { shv[j] = *(const f32x4*)(mp + 256 * j + 4 * lane); sclv[j] = *(const f32x4*)(mp + 1024 + 256 * j + 4 * lane) + 1.0f; } }
.LBB0_239:
	s_waitcnt vmcnt(0)
	v_mov_b32_e32 v130, v96
	v_mov_b32_e32 v131, v97
	v_mov_b32_e32 v132, v98
	v_mov_b32_e32 v133, v99
	v_mov_b32_e32 v134, v100
	v_mov_b32_e32 v135, v101
	v_mov_b32_e32 v136, v102
	v_mov_b32_e32 v137, v103
	s_andn2_b64 vcc, exec, s[16:17]
	s_cbranch_vccnz .LBB0_228
	v_min_i32_e32 v106, 0x8000, v118
	v_ashrrev_i32_e32 v106, 12, v106
	s_mov_b64 vcc, s[76:77]
	s_and_saveexec_b64 s[0:1], vcc
	s_cbranch_execz .LBB0_227
	v_readlane_b32 s36, v253, 23
	v_readlane_b32 s38, v253, 25
	v_readlane_b32 s39, v253, 26
	v_readlane_b32 s37, v253, 24
	s_waitcnt vmcnt(7)
	v_pk_add_f32 v[50:51], v[50:51], 1.0 op_sel_hi:[1,0]
	v_pk_add_f32 v[48:49], v[48:49], 1.0 op_sel_hi:[1,0]
	s_waitcnt vmcnt(6)
	v_pk_add_f32 v[54:55], v[54:55], 1.0 op_sel_hi:[1,0]
	v_pk_add_f32 v[52:53], v[52:53], 1.0 op_sel_hi:[1,0]
	s_waitcnt vmcnt(5)
	v_pk_add_f32 v[58:59], v[58:59], 1.0 op_sel_hi:[1,0]
	v_pk_add_f32 v[56:57], v[56:57], 1.0 op_sel_hi:[1,0]
	s_waitcnt vmcnt(4)
	v_pk_add_f32 v[62:63], v[62:63], 1.0 op_sel_hi:[1,0]
	v_pk_add_f32 v[60:61], v[60:61], 1.0 op_sel_hi:[1,0]
	s_branch .LBB0_227

; DI float hlo(unsigned u) { return (float)__builtin_bit_cast(f16x2_t, u).x; }
; DI float hhi(unsigned u) { return (float)__builtin_bit_cast(f16x2_t, u).y; }
; DI void lnmod_phase(const Args& A, LAS unsigned char* lds, int tid, int bid, int G, bool init, int l_norm, int i_norm, int l_mod, int i_mod, bool want_dt, int nrows, bool ctx_partial, const float* gprev, const float* bprev) {
;     ...
;         for (int j = 0; j < 4; ++j) v[j] = init ? fn[j] : (f32x4){hlo(un[j].x), hhi(un[j].x), hlo(un[j].y), hhi(un[j].y)};
;         { const int rown = row + G * 8;
;           if (rown < nrows) {
;               if (init) { const float* xin = rown < M_LAT ? A.in[I_X] + (size_t)rown * DM : A.in[I_CTX] + (size_t)(rown - M_LAT) * DM;
; #pragma unroll
;                   for (int j = 0; j < 4; ++j) fn[j] = *(const f32x4*)(xin + 256 * j + 4 * lane); }
;               else {
; #pragma unroll
;                   for (int j = 0; j < 4; ++j) un[j] = *(const u32x2*)(X16 + (size_t)rown * DM + 256 * j + 4 * lane); } } }
;         f32x2* STAT = (f32x2*)(A.ws + WS_STAT);
;         if (ctx_partial && row >= M_LAT) {
;             { const f32x2 st = STAT[row];
; #pragma unroll
;               for (int j = 0; j < 4; ++j) v[j] = (v[j] - st.x) * st.y * *(const f32x4*)(gprev + 256 * j + 4 * lane) + *(const f32x4*)(bprev + 256 * j + 4 * lane); }
.Llnmi_skip2:
	v_cvt_f32_f16_sdwa v104, v90 dst_sel:DWORD dst_unused:UNUSED_PAD src0_sel:WORD_1
	v_cvt_f32_f16_e32 v88, v90
	v_cvt_f32_f16_sdwa v89, v91 dst_sel:DWORD dst_unused:UNUSED_PAD src0_sel:WORD_1
	v_cvt_f32_f16_e32 v105, v91
	v_cvt_f32_f16_sdwa v100, v92 dst_sel:DWORD dst_unused:UNUSED_PAD src0_sel:WORD_1
	v_cvt_f32_f16_e32 v90, v92
	v_cvt_f32_f16_sdwa v91, v93 dst_sel:DWORD dst_unused:UNUSED_PAD src0_sel:WORD_1
	v_cvt_f32_f16_e32 v101, v93
	v_cvt_f32_f16_sdwa v95, v96 dst_sel:DWORD dst_unused:UNUSED_PAD src0_sel:WORD_1
	v_cvt_f32_f16_e32 v94, v96
	v_cvt_f32_f16_sdwa v93, v97 dst_sel:DWORD dst_unused:UNUSED_PAD src0_sel:WORD_1
	v_cvt_f32_f16_e32 v92, v97
	v_cvt_f32_f16_sdwa v102, v86 dst_sel:DWORD dst_unused:UNUSED_PAD src0_sel:WORD_1
	v_cvt_f32_f16_e32 v98, v86
	v_cvt_f32_f16_sdwa v106, v87 dst_sel:DWORD dst_unused:UNUSED_PAD src0_sel:WORD_1
	v_cvt_f32_f16_e32 v96, v87
	s_movk_i32 s4, 0x7fff
	v_cmp_lt_i32_e32 vcc, s4, v84
	v_readlane_b32 s4, v253, 37
	v_readlane_b32 s28, v253, 23
	v_readlane_b32 s5, v253, 38
	v_readlane_b32 s30, v253, 25
	v_readlane_b32 s31, v253, 26
	s_and_b64 s[24:25], s[4:5], vcc
	v_readlane_b32 s29, v253, 24
	v_lshl_add_u64 v[86:87], s[30:31], 0, v[64:65]
	s_and_saveexec_b64 s[4:5], s[24:25]
	s_cbranch_execz .LBB0_284
	v_readlane_b32 s26, v253, 25
	v_readlane_b32 s27, v253, 26
	v_add_u32_e32 v146, 0xffff8000, v84
	s_nop 1
	v_lshl_add_u64 v[108:109], s[26:27], 0, v[74:75]
	global_load_dwordx2 v[116:117], v[108:109], off
	v_readlane_b32 s24, v251, 61
	v_readlane_b32 s25, v251, 62
	s_mov_b32 s9, 0x800000
	global_load_dwordx4 v[124:127], v[68:69], off
	global_load_dwordx4 v[112:115], v[70:71], off
	global_load_dwordx4 v[128:131], v[68:69], off offset:1024
	global_load_dwordx4 v[132:135], v[70:71], off offset:1024
	global_load_dwordx4 v[136:139], v[68:69], off offset:2048
	global_load_dwordx4 v[140:143], v[70:71], off offset:2048
	global_load_dwordx4 v[154:157], v[68:69], off offset:3072
	global_load_dwordx4 v[160:163], v[70:71], off offset:3072
	s_waitcnt vmcnt(8)
	v_sub_f32_e32 v109, v104, v116
	v_sub_f32_e32 v108, v88, v116
	v_sub_f32_e32 v88, v105, v116
	v_pk_mul_f32 v[104:105], v[116:117], v[108:109] op_sel:[1,0]
	v_sub_f32_e32 v89, v89, v116
	v_pk_mul_f32 v[88:89], v[116:117], v[88:89] op_sel:[1,0]
	v_sub_f32_e32 v91, v91, v116
	v_sub_f32_e32 v95, v95, v116
	v_sub_f32_e32 v94, v94, v116
	v_sub_f32_e32 v93, v93, v116
	v_sub_f32_e32 v92, v92, v116
	v_sub_f32_e32 v99, v102, v116
	v_sub_f32_e32 v98, v98, v116
	v_sub_f32_e32 v97, v106, v116
	v_sub_f32_e32 v96, v96, v116
	v_pk_mul_f32 v[106:107], v[116:117], v[98:99] op_sel:[1,0]
	s_waitcnt vmcnt(6)
	v_pk_fma_f32 v[120:121], v[124:125], v[104:105], v[112:113]
	v_pk_fma_f32 v[88:89], v[126:127], v[88:89], v[114:115]
	v_sub_f32_e32 v105, v100, v116
	v_sub_f32_e32 v104, v90, v116
	v_sub_f32_e32 v90, v101, v116
	v_pk_mul_f32 v[100:101], v[116:117], v[90:91] op_sel:[1,0]
	v_pk_mul_f32 v[90:91], v[116:117], v[104:105] op_sel:[1,0]
	v_pk_mul_f32 v[104:105], v[116:117], v[94:95] op_sel:[1,0]
	s_waitcnt vmcnt(4)
	v_pk_fma_f32 v[90:91], v[90:91], v[128:129], v[132:133]
	v_pk_fma_f32 v[128:129], v[100:101], v[130:131], v[134:135]
	v_pk_mul_f32 v[100:101], v[116:117], v[92:93] op_sel:[1,0]
	s_waitcnt vmcnt(2)
	v_pk_fma_f32 v[136:137], v[104:105], v[136:137], v[140:141]
	v_pk_fma_f32 v[138:139], v[100:101], v[138:139], v[142:143]
	v_pk_mul_f32 v[104:105], v[116:117], v[96:97] op_sel:[1,0]
	s_waitcnt vmcnt(0)
; DI unsigned pkh2(float lo, float hi) { return __builtin_bit_cast(unsigned, __builtin_amdgcn_cvt_pkrtz(lo, hi)); }
; DI void lnmod_phase(const Args& A, LAS unsigned char* lds, int tid, int bid, int G, bool init, int l_norm, int i_norm, int l_mod, int i_mod, bool want_dt, int nrows, bool ctx_partial, const float* gprev, const float* bprev) {
;     ...
;             const float* t0 = (const float*)(A.ws + WS_T) + (size_t)(row - M_LAT) * DM; const float* t1 = t0 + (size_t)M_CTX * DM; const float* t2 = t1 + (size_t)M_CTX * DM; const float* t3 = t2 + (size_t)M_CTX * DM;
; #pragma unroll
;             for (int j = 0; j < 4; ++j) { v[j] = v[j] * ALPHA + (*(const f32x4*)(t0 + 256 * j + 4 * lane) + *(const f32x4*)(t1 + 256 * j + 4 * lane)) + (*(const f32x4*)(t2 + 256 * j + 4 * lane) + *(const f32x4*)(t3 + 256 * j + 4 * lane)); u32x2 w_; w_.x = pkh2(v[j].x, v[j].y); w_.y = pkh2(v[j].z, v[j].w); *(u32x2*)(xout + 256 * j + 4 * lane) = w_; }
	v_pk_fma_f32 v[154:155], v[106:107], v[154:155], v[160:161]
	v_lshlrev_b64 v[100:101], 12, v[146:147]
	v_lshl_add_u64 v[100:101], s[24:25], 0, v[100:101]
	v_lshlrev_b32_e32 v146, 2, v66
	v_lshl_add_u64 v[106:107], v[100:101], 0, v[146:147]
	v_add_co_u32_e32 v124, vcc, s9, v106
	global_load_dwordx4 v[112:115], v[106:107], off
	s_nop 1
	v_addc_co_u32_e32 v125, vcc, 0, v107, vcc
	global_load_dwordx4 v[116:119], v[124:125], off
	s_mov_b64 s[24:25], 0x800000
	v_lshl_add_u64 v[110:111], v[106:107], 0, s[24:25]
	s_mov_b64 s[24:25], 0x1000000
	v_lshl_add_u64 v[126:127], v[106:107], 0, s[24:25]
	s_mov_b64 s[24:25], 0x1800000
	v_lshl_add_u64 v[132:133], v[106:107], 0, s[24:25]
	s_mov_b32 s9, 0x1000000
	v_add_co_u32_e32 v134, vcc, s9, v106
	s_nop 1
	v_addc_co_u32_e32 v135, vcc, 0, v107, vcc
	s_mov_b32 s9, 0x1800000
	global_load_dwordx4 v[140:143], v[134:135], off
	v_add_co_u32_e32 v164, vcc, s9, v106
	s_nop 1
	v_addc_co_u32_e32 v165, vcc, 0, v107, vcc
	global_load_dwordx4 v[166:169], v[164:165], off
	global_load_dwordx4 v[170:173], v[106:107], off offset:1024
	global_load_dwordx4 v[174:177], v[110:111], off offset:1024
	global_load_dwordx4 v[178:181], v[126:127], off offset:1024
	global_load_dwordx4 v[182:185], v[132:133], off offset:1024
	global_load_dwordx4 v[186:189], v[106:107], off offset:2048
	global_load_dwordx4 v[190:193], v[110:111], off offset:2048
	global_load_dwordx4 v[194:197], v[126:127], off offset:2048
	global_load_dwordx4 v[198:201], v[132:133], off offset:2048
	global_load_dwordx4 v[202:205], v[106:107], off offset:3072
	global_load_dwordx4 v[218:221], v[110:111], off offset:3072
	global_load_dwordx4 v[222:225], v[126:127], off offset:3072
	global_load_dwordx4 v[226:229], v[132:133], off offset:3072
	s_nop 0
	v_pk_fma_f32 v[156:157], v[104:105], v[156:157], v[162:163]
	s_mov_b32 s24, 0x3fd744fd
	s_waitcnt vmcnt(14)
	v_pk_add_f32 v[124:125], v[114:115], v[118:119]
	s_nop 0
	v_pk_fma_f32 v[88:89], v[88:89], s[24:25], v[124:125] op_sel_hi:[1,0,1]
	v_pk_add_f32 v[112:113], v[112:113], v[116:117]
	s_nop 0
	v_pk_fma_f32 v[120:121], v[120:121], s[24:25], v[112:113] op_sel_hi:[1,0,1]
	s_mov_b32 s9, 0x21200000
	s_nop 0
	s_waitcnt vmcnt(12)
	v_pk_add_f32 v[164:165], v[142:143], v[168:169]
	v_pk_add_f32 v[140:141], v[140:141], v[166:167]
	v_pk_add_f32 v[164:165], v[88:89], v[164:165]
	v_pk_add_f32 v[88:89], v[120:121], v[140:141]
	v_add_co_u32_e32 v140, vcc, s9, v86
	v_cvt_pkrtz_f16_f32 v142, v88, v89
	v_cvt_pkrtz_f16_f32 v143, v164, v165
	v_addc_co_u32_e32 v141, vcc, 0, v87, vcc
	global_store_dwordx2 v[140:141], v[142:143], off
	s_nop 0
	s_waitcnt vmcnt(10)
	v_pk_add_f32 v[172:173], v[172:173], v[176:177]
	v_pk_add_f32 v[170:171], v[170:171], v[174:175]
	v_pk_fma_f32 v[128:129], v[128:129], s[24:25], v[172:173] op_sel_hi:[1,0,1]
	v_pk_fma_f32 v[90:91], v[90:91], s[24:25], v[170:171] op_sel_hi:[1,0,1]
	s_waitcnt vmcnt(8)
	v_pk_add_f32 v[180:181], v[180:181], v[184:185]
	v_pk_add_f32 v[178:179], v[178:179], v[182:183]
	v_pk_add_f32 v[122:123], v[128:129], v[180:181]
	v_pk_add_f32 v[90:91], v[90:91], v[178:179]
	v_cvt_pkrtz_f16_f32 v129, v122, v123
	v_cvt_pkrtz_f16_f32 v128, v90, v91
	global_store_dwordx2 v[140:141], v[128:129], off offset:512
	s_waitcnt vmcnt(6)
	v_pk_add_f32 v[128:129], v[188:189], v[192:193]
	v_pk_add_f32 v[186:187], v[186:187], v[190:191]
	v_pk_fma_f32 v[128:129], v[138:139], s[24:25], v[128:129] op_sel_hi:[1,0,1]
	v_pk_fma_f32 v[190:191], v[136:137], s[24:25], v[186:187] op_sel_hi:[1,0,1]
	s_waitcnt vmcnt(4)
	v_pk_add_f32 v[196:197], v[196:197], v[200:201]
	v_pk_add_f32 v[198:199], v[194:195], v[198:199]
	v_pk_add_f32 v[194:195], v[128:129], v[196:197]
	v_pk_add_f32 v[196:197], v[190:191], v[198:199]
	v_cvt_pkrtz_f16_f32 v129, v194, v195
	v_cvt_pkrtz_f16_f32 v128, v196, v197
	global_store_dwordx2 v[140:141], v[128:129], off offset:1024
	s_nop 0
	s_waitcnt vmcnt(2)
	v_pk_add_f32 v[204:205], v[204:205], v[220:221]
	v_pk_add_f32 v[202:203], v[202:203], v[218:219]
	v_pk_fma_f32 v[204:205], v[156:157], s[24:25], v[204:205] op_sel_hi:[1,0,1]
	v_pk_fma_f32 v[202:203], v[154:155], s[24:25], v[202:203] op_sel_hi:[1,0,1]
	s_nop 0
	s_waitcnt vmcnt(0)
	v_pk_add_f32 v[224:225], v[224:225], v[228:229]
	v_pk_add_f32 v[226:227], v[222:223], v[226:227]
	v_pk_add_f32 v[222:223], v[204:205], v[224:225]
	v_pk_add_f32 v[224:225], v[202:203], v[226:227]
	v_cvt_pkrtz_f16_f32 v227, v222, v223
	v_cvt_pkrtz_f16_f32 v226, v224, v225
	global_store_dwordx2 v[140:141], v[226:227], off offset:1536
	v_mov_b32_e32 v228, v89
	v_mov_b32_e32 v229, v164
	v_mov_b32_e32 v89, v165
	v_mov_b32_e32 v164, v91
	v_mov_b32_e32 v165, v122
	v_mov_b32_e32 v91, v123
	v_mov_b32_e32 v226, v225
	v_mov_b32_e32 v202, v223
	v_mov_b32_e32 v92, v194
	v_mov_b32_e32 v93, v195
	v_mov_b32_e32 v94, v196
	v_mov_b32_e32 v95, v197
	v_mov_b32_e32 v96, v222
	v_mov_b32_e32 v98, v224
	v_mov_b32_e32 v100, v164
	v_mov_b32_e32 v101, v165
	v_mov_b32_e32 v102, v226
	v_mov_b32_e32 v104, v228
	v_mov_b32_e32 v105, v229
	v_mov_b32_e32 v106, v202

; DI void lnmod_phase(const Args& A, LAS unsigned char* lds, int tid, int bid, int G, bool init, int l_norm, int i_norm, int l_mod, int i_mod, bool want_dt, int nrows, bool ctx_partial, const float* gprev, const float* bprev) {
;     ...
;         if (l_mod >= 0) {
;             const int mi = row < M_LAT ? (row >> 12) : 8;
;             const float* mp = MOD + ((size_t)l_mod * 9 + mi) * 9216 + i_mod * 3072;
;             if (mi != mi_cur) { mi_cur = mi;
; #pragma unroll
;                 for (int j = 0; j < 4; ++j) { shv[j] = *(const f32x4*)(mp + 256 * j + 4 * lane); sclv[j] = *(const f32x4*)(mp + 1024 + 256 * j + 4 * lane) + 1.0f; } }
.LBB0_287:
	s_or_b64 exec, exec, s[4:5]
	s_waitcnt vmcnt(0)
	v_mov_b32_e32 v124, v76
	v_mov_b32_e32 v125, v77
	v_mov_b32_e32 v126, v78
	v_mov_b32_e32 v127, v79
	v_mov_b32_e32 v128, v80
	v_mov_b32_e32 v129, v81
	v_mov_b32_e32 v130, v82
	v_mov_b32_e32 v131, v83
	v_min_i32_e32 v84, 0x8000, v84
	v_ashrrev_i32_e32 v84, 12, v84
	s_mov_b64 vcc, s[76:77]
	s_and_saveexec_b64 s[4:5], vcc
	s_cbranch_execz .LBB0_278
	v_readlane_b32 s24, v252, 7
	v_readlane_b32 s25, v252, 8
	s_waitcnt vmcnt(7)
	v_pk_add_f32 v[50:51], v[50:51], 1.0 op_sel_hi:[1,0]
	v_pk_add_f32 v[48:49], v[48:49], 1.0 op_sel_hi:[1,0]
	s_waitcnt vmcnt(6)
	v_pk_add_f32 v[54:55], v[54:55], 1.0 op_sel_hi:[1,0]
	v_pk_add_f32 v[52:53], v[52:53], 1.0 op_sel_hi:[1,0]
	s_waitcnt vmcnt(5)
	v_pk_add_f32 v[58:59], v[58:59], 1.0 op_sel_hi:[1,0]
	v_pk_add_f32 v[56:57], v[56:57], 1.0 op_sel_hi:[1,0]
	s_waitcnt vmcnt(4)
	v_pk_add_f32 v[62:63], v[62:63], 1.0 op_sel_hi:[1,0]
	v_pk_add_f32 v[60:61], v[60:61], 1.0 op_sel_hi:[1,0]
	s_branch .LBB0_278
